# attention strip: xor-16/xor-32 reductions (row max, q-norm sum) via v_permlane16_swap / v_permlane32_swap instead of ds_bpermute round trips
# speedup vs baseline: 1.0032x; 1.0019x over previous
; DI u32x4 pack8(const float* f) { u32x4 w; w.x = pk2(f[0], f[1]); w.y = pk2(f[2], f[3]); w.z = pk2(f[4], f[5]); w.w = pk2(f[6], f[7]); return w; }
; DI void attn_item(const Params& p, const Ctx& c, int l, int S, int tokbase, int qb, int kvh) {
;     ...
;         mx = fmaxf(mx, __shfl_xor(mx, 16)); mx = fmaxf(mx, __shfl_xor(mx, 32));
;         float sum = 0.f;
; #pragma unroll
;         for (int t = 0; t < 17; ++t)
; #pragma unroll
;             for (int r = 0; r < 4; ++r) { const float pv = __builtin_amdgcn_exp2f(s[t][r] - mx); s[t][r] = pv; sum += pv; }
;         sum += __shfl_xor(sum, 16); sum += __shfl_xor(sum, 32);
;         sum += __builtin_amdgcn_exp2f(sink - mx);
;     ...
;             const bf16x8 bfr = __builtin_bit_cast(bf16x8, pack8(g));
.LBB0_316:
	v_mov_b32_e32 v216, v188
	v_add_u32_e32 v108, 0x900, v108
	v_add_u32_e32 v102, 0x100, v102
	v_permlane16_swap_b32_e32 v216, v188
	v_max_f32_e32 v216, v216, v188
	v_mov_b32_e32 v217, v216
	s_nop 1
	v_permlane32_swap_b32_e32 v217, v216
	v_max_f32_e32 v218, v217, v216
	s_nop 0
	v_pk_add_f32 v[26:27], v[26:27], v[218:219] op_sel_hi:[1,0] neg_lo:[0,1] neg_hi:[0,1]
	v_pk_add_f32 v[28:29], v[28:29], v[218:219] op_sel_hi:[1,0] neg_lo:[0,1] neg_hi:[0,1]
	v_pk_add_f32 v[30:31], v[30:31], v[218:219] op_sel_hi:[1,0] neg_lo:[0,1] neg_hi:[0,1]
	v_pk_add_f32 v[32:33], v[32:33], v[218:219] op_sel_hi:[1,0] neg_lo:[0,1] neg_hi:[0,1]
	v_pk_add_f32 v[34:35], v[34:35], v[218:219] op_sel_hi:[1,0] neg_lo:[0,1] neg_hi:[0,1]
	v_pk_add_f32 v[36:37], v[36:37], v[218:219] op_sel_hi:[1,0] neg_lo:[0,1] neg_hi:[0,1]
	v_pk_add_f32 v[38:39], v[38:39], v[218:219] op_sel_hi:[1,0] neg_lo:[0,1] neg_hi:[0,1]
	v_pk_add_f32 v[40:41], v[40:41], v[218:219] op_sel_hi:[1,0] neg_lo:[0,1] neg_hi:[0,1]
	v_pk_add_f32 v[42:43], v[42:43], v[218:219] op_sel_hi:[1,0] neg_lo:[0,1] neg_hi:[0,1]
	v_pk_add_f32 v[44:45], v[44:45], v[218:219] op_sel_hi:[1,0] neg_lo:[0,1] neg_hi:[0,1]
	v_pk_add_f32 v[46:47], v[46:47], v[218:219] op_sel_hi:[1,0] neg_lo:[0,1] neg_hi:[0,1]
	v_pk_add_f32 v[48:49], v[48:49], v[218:219] op_sel_hi:[1,0] neg_lo:[0,1] neg_hi:[0,1]
	v_pk_add_f32 v[50:51], v[50:51], v[218:219] op_sel_hi:[1,0] neg_lo:[0,1] neg_hi:[0,1]
	v_pk_add_f32 v[52:53], v[52:53], v[218:219] op_sel_hi:[1,0] neg_lo:[0,1] neg_hi:[0,1]
	v_pk_add_f32 v[54:55], v[54:55], v[218:219] op_sel_hi:[1,0] neg_lo:[0,1] neg_hi:[0,1]
	v_pk_add_f32 v[56:57], v[56:57], v[218:219] op_sel_hi:[1,0] neg_lo:[0,1] neg_hi:[0,1]
	v_pk_add_f32 v[58:59], v[58:59], v[218:219] op_sel_hi:[1,0] neg_lo:[0,1] neg_hi:[0,1]
	v_pk_add_f32 v[60:61], v[60:61], v[218:219] op_sel_hi:[1,0] neg_lo:[0,1] neg_hi:[0,1]
	v_pk_add_f32 v[62:63], v[62:63], v[218:219] op_sel_hi:[1,0] neg_lo:[0,1] neg_hi:[0,1]
	v_pk_add_f32 v[64:65], v[64:65], v[218:219] op_sel_hi:[1,0] neg_lo:[0,1] neg_hi:[0,1]
	v_pk_add_f32 v[66:67], v[66:67], v[218:219] op_sel_hi:[1,0] neg_lo:[0,1] neg_hi:[0,1]
	v_pk_add_f32 v[68:69], v[68:69], v[218:219] op_sel_hi:[1,0] neg_lo:[0,1] neg_hi:[0,1]
	v_pk_add_f32 v[70:71], v[70:71], v[218:219] op_sel_hi:[1,0] neg_lo:[0,1] neg_hi:[0,1]
	v_pk_add_f32 v[72:73], v[72:73], v[218:219] op_sel_hi:[1,0] neg_lo:[0,1] neg_hi:[0,1]
	v_pk_add_f32 v[74:75], v[74:75], v[218:219] op_sel_hi:[1,0] neg_lo:[0,1] neg_hi:[0,1]
	v_pk_add_f32 v[76:77], v[76:77], v[218:219] op_sel_hi:[1,0] neg_lo:[0,1] neg_hi:[0,1]
	v_pk_add_f32 v[78:79], v[78:79], v[218:219] op_sel_hi:[1,0] neg_lo:[0,1] neg_hi:[0,1]
	v_pk_add_f32 v[80:81], v[80:81], v[218:219] op_sel_hi:[1,0] neg_lo:[0,1] neg_hi:[0,1]
	v_pk_add_f32 v[82:83], v[82:83], v[218:219] op_sel_hi:[1,0] neg_lo:[0,1] neg_hi:[0,1]
	v_pk_add_f32 v[84:85], v[84:85], v[218:219] op_sel_hi:[1,0] neg_lo:[0,1] neg_hi:[0,1]
	v_pk_add_f32 v[86:87], v[86:87], v[218:219] op_sel_hi:[1,0] neg_lo:[0,1] neg_hi:[0,1]
	v_pk_add_f32 v[88:89], v[88:89], v[218:219] op_sel_hi:[1,0] neg_lo:[0,1] neg_hi:[0,1]
	v_pk_add_f32 v[90:91], v[90:91], v[218:219] op_sel_hi:[1,0] neg_lo:[0,1] neg_hi:[0,1]
	v_pk_add_f32 v[92:93], v[92:93], v[218:219] op_sel_hi:[1,0] neg_lo:[0,1] neg_hi:[0,1]
	v_exp_f32_e32 v26, v26
	v_exp_f32_e32 v27, v27
	v_exp_f32_e32 v28, v28
	v_exp_f32_e32 v29, v29
	v_exp_f32_e32 v30, v30
	v_exp_f32_e32 v31, v31
	v_exp_f32_e32 v32, v32
	v_exp_f32_e32 v33, v33
	v_exp_f32_e32 v34, v34
	v_exp_f32_e32 v35, v35
	v_exp_f32_e32 v36, v36
	v_exp_f32_e32 v37, v37
	v_exp_f32_e32 v38, v38
	v_exp_f32_e32 v39, v39
	v_exp_f32_e32 v40, v40
	v_exp_f32_e32 v41, v41
	v_exp_f32_e32 v42, v42
	v_exp_f32_e32 v43, v43
	v_exp_f32_e32 v44, v44
	v_exp_f32_e32 v45, v45
	v_exp_f32_e32 v46, v46
	v_exp_f32_e32 v47, v47
	v_exp_f32_e32 v48, v48
	v_exp_f32_e32 v49, v49
	v_exp_f32_e32 v50, v50
	v_exp_f32_e32 v51, v51
	v_exp_f32_e32 v52, v52
	v_exp_f32_e32 v53, v53
	v_exp_f32_e32 v54, v54
	v_exp_f32_e32 v55, v55
	v_exp_f32_e32 v56, v56
	v_exp_f32_e32 v57, v57
	v_exp_f32_e32 v58, v58
	v_exp_f32_e32 v59, v59
	v_exp_f32_e32 v60, v60
	v_exp_f32_e32 v61, v61
	v_exp_f32_e32 v62, v62
	v_exp_f32_e32 v63, v63
	v_exp_f32_e32 v64, v64
	v_exp_f32_e32 v65, v65
	v_exp_f32_e32 v66, v66
	v_exp_f32_e32 v67, v67
	v_exp_f32_e32 v68, v68
	v_exp_f32_e32 v69, v69
	v_exp_f32_e32 v70, v70
	v_exp_f32_e32 v71, v71
	v_exp_f32_e32 v72, v72
	v_exp_f32_e32 v73, v73
	v_exp_f32_e32 v74, v74
	v_exp_f32_e32 v75, v75
	v_exp_f32_e32 v76, v76
	v_exp_f32_e32 v77, v77
	v_exp_f32_e32 v78, v78
	v_exp_f32_e32 v79, v79
	v_exp_f32_e32 v80, v80
	v_exp_f32_e32 v81, v81
	v_exp_f32_e32 v82, v82
	v_exp_f32_e32 v83, v83
	v_exp_f32_e32 v84, v84
	v_exp_f32_e32 v85, v85
	v_exp_f32_e32 v86, v86
	v_exp_f32_e32 v87, v87
	v_exp_f32_e32 v88, v88
	v_exp_f32_e32 v89, v89
	v_exp_f32_e32 v90, v90
	v_exp_f32_e32 v91, v91
	v_exp_f32_e32 v92, v92
	v_exp_f32_e32 v93, v93
	v_pk_add_f32 v[220:221], v[26:27], v[28:29]
	v_pk_add_f32 v[220:221], v[220:221], v[30:31]
	v_pk_add_f32 v[220:221], v[220:221], v[32:33]
	v_pk_add_f32 v[220:221], v[220:221], v[34:35]
	v_pk_add_f32 v[220:221], v[220:221], v[36:37]
	v_pk_add_f32 v[220:221], v[220:221], v[38:39]
	v_pk_add_f32 v[220:221], v[220:221], v[40:41]
	v_pk_add_f32 v[220:221], v[220:221], v[42:43]
	v_pk_add_f32 v[220:221], v[220:221], v[44:45]
	v_pk_add_f32 v[220:221], v[220:221], v[46:47]
	v_pk_add_f32 v[220:221], v[220:221], v[48:49]
	v_pk_add_f32 v[220:221], v[220:221], v[50:51]
	v_pk_add_f32 v[220:221], v[220:221], v[52:53]
	v_pk_add_f32 v[220:221], v[220:221], v[54:55]
	v_pk_add_f32 v[220:221], v[220:221], v[56:57]
	v_pk_add_f32 v[220:221], v[220:221], v[58:59]
	v_pk_add_f32 v[220:221], v[220:221], v[60:61]
	v_pk_add_f32 v[220:221], v[220:221], v[62:63]
	v_pk_add_f32 v[220:221], v[220:221], v[64:65]
	v_pk_add_f32 v[220:221], v[220:221], v[66:67]
	v_pk_add_f32 v[220:221], v[220:221], v[68:69]
	v_pk_add_f32 v[220:221], v[220:221], v[70:71]
	v_pk_add_f32 v[220:221], v[220:221], v[72:73]
	v_pk_add_f32 v[220:221], v[220:221], v[74:75]
	v_pk_add_f32 v[220:221], v[220:221], v[76:77]
	v_pk_add_f32 v[220:221], v[220:221], v[78:79]
	v_pk_add_f32 v[220:221], v[220:221], v[80:81]
	v_pk_add_f32 v[220:221], v[220:221], v[82:83]
	v_pk_add_f32 v[220:221], v[220:221], v[84:85]
	v_pk_add_f32 v[220:221], v[220:221], v[86:87]
	v_pk_add_f32 v[220:221], v[220:221], v[88:89]
	v_pk_add_f32 v[220:221], v[220:221], v[90:91]
	v_pk_add_f32 v[220:221], v[220:221], v[92:93]
	v_add_f32_e32 v224, v220, v221
	ds_bpermute_b32 v225, v104, v224
	v_sub_f32_e32 v222, v106, v218
	v_cvt_pk_bf16_f32 v130, v26, v27
	v_cvt_pk_bf16_f32 v131, v28, v29
	v_cvt_pk_bf16_f32 v132, v30, v31
	v_cvt_pk_bf16_f32 v133, v32, v33
	v_cvt_pk_bf16_f32 v134, v34, v35
	v_cvt_pk_bf16_f32 v135, v36, v37
	v_cvt_pk_bf16_f32 v136, v38, v39
	v_cvt_pk_bf16_f32 v137, v40, v41
	v_cvt_pk_bf16_f32 v138, v42, v43
	v_cvt_pk_bf16_f32 v139, v44, v45
	v_cvt_pk_bf16_f32 v140, v46, v47
	v_cvt_pk_bf16_f32 v141, v48, v49
	s_waitcnt lgkmcnt(0)
; #define LAS __attribute__((address_space(3)))
; DI u32x4 pack8(const float* f) { u32x4 w; w.x = pk2(f[0], f[1]); w.y = pk2(f[2], f[3]); w.z = pk2(f[4], f[5]); w.w = pk2(f[6], f[7]); return w; }
; DI void attn_item(const Params& p, const Ctx& c, int l, int S, int tokbase, int qb, int kvh) {
;     ...
;         sum += __shfl_xor(sum, 16); sum += __shfl_xor(sum, 32);
;         sum += __builtin_amdgcn_exp2f(sink - mx);
;         f32x4 o[4];
; #pragma unroll
;         for (int dt = 0; dt < 4; ++dt) o[dt] = (f32x4){0.f, 0.f, 0.f, 0.f};
; #pragma unroll
;         for (int u = 0; u < 9; ++u) {
;             float g[8];
; #pragma unroll
;             for (int r = 0; r < 4; ++r) { g[r] = s[2 * u][r]; g[4 + r] = (2 * u + 1 < 17) ? s[(2 * u + 1 < 17) ? 2 * u + 1 : 0][r] : 0.f; }
;             const bf16x8 bfr = __builtin_bit_cast(bf16x8, pack8(g));
; #pragma unroll
;             for (int dt = 0; dt < 4; ++dt) {
;                 const LAS bf16_t* vr = VTs + (dt * 16 + lr) * VP + (kt0 + 2 * u) * 16 + lg * 4;
;                 const s16x4 lo = *(const LAS s16x4*)vr;
;                 s16x4 hi = (s16x4){0, 0, 0, 0};
;                 if (2 * u + 1 < 17) hi = *(const LAS s16x4*)(vr + 16);
;                 o[dt] = __builtin_amdgcn_mfma_f32_16x16x32_bf16(__builtin_shufflevector(lo, hi, 0, 1, 2, 3, 4, 5, 6, 7), bfr, o[dt], 0, 0, 0); }
	v_add_f32_e32 v225, v224, v225
	v_exp_f32_e32 v224, v222
	ds_bpermute_b32 v122, v105, v225
	v_cvt_pk_bf16_f32 v142, v50, v51
	v_cvt_pk_bf16_f32 v143, v52, v53
	v_cvt_pk_bf16_f32 v144, v54, v55
	v_cvt_pk_bf16_f32 v145, v56, v57
	v_cvt_pk_bf16_f32 v146, v58, v59
	v_cvt_pk_bf16_f32 v147, v60, v61
	v_cvt_pk_bf16_f32 v148, v62, v63
	v_cvt_pk_bf16_f32 v149, v64, v65
	v_cvt_pk_bf16_f32 v150, v66, v67
	v_cvt_pk_bf16_f32 v151, v68, v69
	v_cvt_pk_bf16_f32 v152, v70, v71
	v_cvt_pk_bf16_f32 v153, v72, v73
	v_cvt_pk_bf16_f32 v154, v74, v75
	v_cvt_pk_bf16_f32 v155, v76, v77
	v_cvt_pk_bf16_f32 v156, v78, v79
	v_cvt_pk_bf16_f32 v157, v80, v81
	v_cvt_pk_bf16_f32 v158, v82, v83
	v_cvt_pk_bf16_f32 v159, v84, v85
	v_cvt_pk_bf16_f32 v160, v86, v87
	v_cvt_pk_bf16_f32 v161, v88, v89
	v_cvt_pk_bf16_f32 v162, v90, v91
	v_cvt_pk_bf16_f32 v163, v92, v93
	v_mov_b32_e32 v164, 0
	v_mov_b32_e32 v165, 0
	v_add_u32_e32 v123, 0xd800, v107
	v_add_u32_e32 v124, 0x10900, v107
	v_add_u32_e32 v125, 0x13a00, v107
	v_add_u32_e32 v126, 0x16b00, v107
	v_add_u32_e32 v107, 32, v107
	ds_read2_b64 v[48:51], v123 offset1:4
	ds_read2_b64 v[52:55], v124 offset1:4
	ds_read2_b64 v[56:59], v125 offset1:4
	ds_read2_b64 v[60:63], v126 offset1:4
	ds_read2_b64 v[64:67], v123 offset0:8 offset1:12
	ds_read2_b64 v[68:71], v124 offset0:8 offset1:12
	ds_read2_b64 v[72:75], v125 offset0:8 offset1:12
	ds_read2_b64 v[76:79], v126 offset0:8 offset1:12
	ds_read2_b64 v[80:83], v123 offset0:16 offset1:20
	ds_read2_b64 v[84:87], v124 offset0:16 offset1:20
	ds_read2_b64 v[88:91], v125 offset0:16 offset1:20
	ds_read2_b64 v[92:95], v126 offset0:16 offset1:20
	s_waitcnt lgkmcnt(8)
	v_add_f32_e32 v225, v225, v122
	v_mfma_f32_16x16x32_bf16 v[42:45], v[48:51], v[130:133], 0
	v_mfma_f32_16x16x32_bf16 v[38:41], v[52:55], v[130:133], 0
	v_mfma_f32_16x16x32_bf16 v[34:37], v[56:59], v[130:133], 0
	v_mfma_f32_16x16x32_bf16 v[26:29], v[60:63], v[130:133], 0
	ds_read2_b64 v[48:51], v123 offset0:24 offset1:28
	ds_read2_b64 v[52:55], v124 offset0:24 offset1:28
	ds_read2_b64 v[56:59], v125 offset0:24 offset1:28
	ds_read2_b64 v[60:63], v126 offset0:24 offset1:28
	s_waitcnt lgkmcnt(8)
	v_mfma_f32_16x16x32_bf16 v[42:45], v[64:67], v[134:137], v[42:45]
	v_mfma_f32_16x16x32_bf16 v[38:41], v[68:71], v[134:137], v[38:41]
	v_mfma_f32_16x16x32_bf16 v[34:37], v[72:75], v[134:137], v[34:37]
	v_mfma_f32_16x16x32_bf16 v[26:29], v[76:79], v[134:137], v[26:29]
	ds_read2_b64 v[64:67], v123 offset0:32 offset1:36
	ds_read2_b64 v[68:71], v124 offset0:32 offset1:36
	ds_read2_b64 v[72:75], v125 offset0:32 offset1:36
	ds_read2_b64 v[76:79], v126 offset0:32 offset1:36
	s_waitcnt lgkmcnt(8)
	v_mfma_f32_16x16x32_bf16 v[42:45], v[80:83], v[138:141], v[42:45]
	v_mfma_f32_16x16x32_bf16 v[38:41], v[84:87], v[138:141], v[38:41]
	v_mfma_f32_16x16x32_bf16 v[34:37], v[88:91], v[138:141], v[34:37]
	v_mfma_f32_16x16x32_bf16 v[26:29], v[92:95], v[138:141], v[26:29]
	ds_read2_b64 v[80:83], v123 offset0:40 offset1:44
	ds_read2_b64 v[84:87], v124 offset0:40 offset1:44
	ds_read2_b64 v[88:91], v125 offset0:40 offset1:44
	ds_read2_b64 v[92:95], v126 offset0:40 offset1:44
	s_waitcnt lgkmcnt(8)
	v_mfma_f32_16x16x32_bf16 v[42:45], v[48:51], v[142:145], v[42:45]
	v_mfma_f32_16x16x32_bf16 v[38:41], v[52:55], v[142:145], v[38:41]
	v_mfma_f32_16x16x32_bf16 v[34:37], v[56:59], v[142:145], v[34:37]
	v_mfma_f32_16x16x32_bf16 v[26:29], v[60:63], v[142:145], v[26:29]
	ds_read2_b64 v[48:51], v123 offset0:48 offset1:52
	ds_read2_b64 v[52:55], v124 offset0:48 offset1:52
	ds_read2_b64 v[56:59], v125 offset0:48 offset1:52
	ds_read2_b64 v[60:63], v126 offset0:48 offset1:52
	s_waitcnt lgkmcnt(8)
; #define LAS __attribute__((address_space(3)))
; DI unsigned pk2(float lo, float hi) { const f2_t v = {lo, hi}; const bf2_t r = __builtin_convertvector(v, bf2_t); return __builtin_bit_cast(unsigned, r); }
; DI u32x4 pack8(const float* f) { u32x4 w; w.x = pk2(f[0], f[1]); w.y = pk2(f[2], f[3]); w.z = pk2(f[4], f[5]); w.w = pk2(f[6], f[7]); return w; }
;     DI bf16_t* fOUTS() const { return (bf16_t*)(ws + WS_OUTS); }
; DI void attn_item(const Params& p, const Ctx& c, int l, int S, int tokbase, int qb, int kvh) {
;     ...
;         for (int u = 0; u < 9; ++u) {
;             float g[8];
; #pragma unroll
;             for (int r = 0; r < 4; ++r) { g[r] = s[2 * u][r]; g[4 + r] = (2 * u + 1 < 17) ? s[(2 * u + 1 < 17) ? 2 * u + 1 : 0][r] : 0.f; }
;             const bf16x8 bfr = __builtin_bit_cast(bf16x8, pack8(g));
; #pragma unroll
;             for (int dt = 0; dt < 4; ++dt) {
;                 const LAS bf16_t* vr = VTs + (dt * 16 + lr) * VP + (kt0 + 2 * u) * 16 + lg * 4;
;                 const s16x4 lo = *(const LAS s16x4*)vr;
;                 s16x4 hi = (s16x4){0, 0, 0, 0};
;                 if (2 * u + 1 < 17) hi = *(const LAS s16x4*)(vr + 16);
;                 o[dt] = __builtin_amdgcn_mfma_f32_16x16x32_bf16(__builtin_shufflevector(lo, hi, 0, 1, 2, 3, 4, 5, 6, 7), bfr, o[dt], 0, 0, 0); }
;         }
;         const float inv = 1.f / sum;
;         bf16_t* op = c.fOUTS() + (size_t)(tokbase + qpos) * OLD + head * 64 + lg * 4;
; #pragma unroll
;         for (int dt = 0; dt < 4; ++dt) { u32x2 ov; ov.x = pk2(o[dt][0] * inv, o[dt][1] * inv); ov.y = pk2(o[dt][2] * inv, o[dt][3] * inv); *(u32x2*)(op + dt * 16) = ov; }
	v_mfma_f32_16x16x32_bf16 v[42:45], v[64:67], v[146:149], v[42:45]
	v_mfma_f32_16x16x32_bf16 v[38:41], v[68:71], v[146:149], v[38:41]
	v_mfma_f32_16x16x32_bf16 v[34:37], v[72:75], v[146:149], v[34:37]
	v_mfma_f32_16x16x32_bf16 v[26:29], v[76:79], v[146:149], v[26:29]
	ds_read2_b64 v[64:67], v123 offset0:56 offset1:60
	ds_read2_b64 v[68:71], v124 offset0:56 offset1:60
	ds_read2_b64 v[72:75], v125 offset0:56 offset1:60
	ds_read2_b64 v[76:79], v126 offset0:56 offset1:60
	s_waitcnt lgkmcnt(8)
	v_mfma_f32_16x16x32_bf16 v[42:45], v[80:83], v[150:153], v[42:45]
	v_mfma_f32_16x16x32_bf16 v[38:41], v[84:87], v[150:153], v[38:41]
	v_mfma_f32_16x16x32_bf16 v[34:37], v[88:91], v[150:153], v[34:37]
	v_mfma_f32_16x16x32_bf16 v[26:29], v[92:95], v[150:153], v[26:29]
	ds_read_b64 v[80:81], v123 offset:512
	ds_read_b64 v[84:85], v124 offset:512
	ds_read_b64 v[88:89], v125 offset:512
	ds_read_b64 v[92:93], v126 offset:512
	v_mov_b64_e32 v[82:83], 0
	v_mov_b64_e32 v[86:87], 0
	v_mov_b64_e32 v[90:91], 0
	v_mov_b64_e32 v[94:95], 0
	s_waitcnt lgkmcnt(8)
	v_mfma_f32_16x16x32_bf16 v[42:45], v[48:51], v[154:157], v[42:45]
	v_mfma_f32_16x16x32_bf16 v[38:41], v[52:55], v[154:157], v[38:41]
	v_mfma_f32_16x16x32_bf16 v[34:37], v[56:59], v[154:157], v[34:37]
	v_mfma_f32_16x16x32_bf16 v[26:29], v[60:63], v[154:157], v[26:29]
	s_waitcnt lgkmcnt(4)
	v_mfma_f32_16x16x32_bf16 v[42:45], v[64:67], v[158:161], v[42:45]
	v_mfma_f32_16x16x32_bf16 v[38:41], v[68:71], v[158:161], v[38:41]
	v_mfma_f32_16x16x32_bf16 v[34:37], v[72:75], v[158:161], v[34:37]
	v_mfma_f32_16x16x32_bf16 v[26:29], v[76:79], v[158:161], v[26:29]
	s_waitcnt lgkmcnt(0)
	v_mfma_f32_16x16x32_bf16 v[42:45], v[80:83], v[162:165], v[42:45]
	v_mfma_f32_16x16x32_bf16 v[38:41], v[84:87], v[162:165], v[38:41]
	v_mfma_f32_16x16x32_bf16 v[34:37], v[88:91], v[162:165], v[34:37]
	v_mfma_f32_16x16x32_bf16 v[26:29], v[92:95], v[162:165], v[26:29]
	v_add_f32_e32 v30, v224, v225
	v_div_scale_f32 v31, s[20:21], v30, v30, 1.0
	v_rcp_f32_e32 v32, v31
	s_nop 0
	v_fma_f32 v33, -v31, v32, 1.0
	v_fmac_f32_e32 v32, v33, v32
	v_div_scale_f32 v33, vcc, 1.0, v30, 1.0
	v_mul_f32_e32 v46, v33, v32
	v_fma_f32 v47, -v31, v46, v33
	v_fmac_f32_e32 v46, v47, v32
	v_fma_f32 v31, -v31, v46, v33
	v_div_fmas_f32 v31, v31, v32, v46
	v_div_fixup_f32 v30, v31, v30, 1.0
	v_add_u32_e32 v31, s40, v1
	v_pk_mul_f32 v[42:43], v[30:31], v[42:43] op_sel_hi:[0,1]
	v_pk_mul_f32 v[44:45], v[30:31], v[44:45] op_sel_hi:[0,1]
	v_pk_mul_f32 v[38:39], v[30:31], v[38:39] op_sel_hi:[0,1]
	v_pk_mul_f32 v[40:41], v[30:31], v[40:41] op_sel_hi:[0,1]
	v_pk_mul_f32 v[34:35], v[30:31], v[34:35] op_sel_hi:[0,1]
	v_pk_mul_f32 v[36:37], v[30:31], v[36:37] op_sel_hi:[0,1]
	v_pk_mul_f32 v[26:27], v[30:31], v[26:27] op_sel_hi:[0,1]
	v_pk_mul_f32 v[28:29], v[30:31], v[28:29] op_sel_hi:[0,1]
	v_mad_i64_i32 v[32:33], s[20:21], v31, s22, v[98:99]
	v_cvt_pk_bf16_f32 v42, v42, v43
	v_cvt_pk_bf16_f32 v43, v44, v45
	v_cvt_pk_bf16_f32 v38, v38, v39
	v_cvt_pk_bf16_f32 v39, v40, v41
	v_cvt_pk_bf16_f32 v34, v34, v35
	v_cvt_pk_bf16_f32 v35, v36, v37
	v_cvt_pk_bf16_f32 v26, v26, v27
	v_cvt_pk_bf16_f32 v27, v28, v29
	global_store_dwordx2 v[32:33], v[42:43], off
	global_store_dwordx2 v[32:33], v[38:39], off offset:32
	global_store_dwordx2 v[32:33], v[34:35], off offset:64
	global_store_dwordx2 v[32:33], v[26:27], off offset:96
	s_mov_b64 s[20:21], 0x18000
	s_add_i32 s40, s40, 16
	s_waitcnt vmcnt(8)
	v_mov_b64_e32 v[32:33], v[24:25]
	v_mov_b64_e32 v[28:29], v[20:21]
	v_lshl_add_u64 v[100:101], v[100:101], 0, s[20:21]
	s_cmp_lg_u32 s40, 64
	v_mov_b64_e32 v[30:31], v[22:23]
	v_mov_b64_e32 v[26:27], v[18:19]
	s_cbranch_scc0 .LBB0_323

; DI u32x4 pack8(const float* f) { u32x4 w; w.x = pk2(f[0], f[1]); w.y = pk2(f[2], f[3]); w.z = pk2(f[4], f[5]); w.w = pk2(f[6], f[7]); return w; }
;     DI float* fROPE() const { return (float*)(ws + WS_ROPE); }
; DI void attn_item(const Params& p, const Ctx& c, int l, int S, int tokbase, int qb, int kvh) {
;     ...
;         const int qi = qh * 64 + 16 * j + lr, qpos = qb * 128 + qi, kt0 = qh * 4 + j;
;         float f0[8], f1[8]; unpack8(nq0, f0); unpack8(nq1, f1);
;         if (j < 3) { nq0 = *(const u32x4*)(qbase + (size_t)(16 * (j + 1)) * P1LD); nq1 = *(const u32x4*)(qbase + (size_t)(16 * (j + 1)) * P1LD + 32); }
;         float ss = 0.f;
; #pragma unroll
;         for (int i = 0; i < 8; ++i) ss += f0[i] * f0[i] + f1[i] * f1[i];
;         ss += __shfl_xor(ss, 16); ss += __shfl_xor(ss, 32);
;         const float rstd = rsqrtf(ss * (1.f / 64.f) + EPS);
; #pragma unroll
;         for (int i = 0; i < 8; ++i) { f0[i] *= rstd * g0[i]; f1[i] *= rstd * g1[i]; }
;         const float* rr = c.fROPE() + qpos * 16;
; #pragma unroll
;         for (int i = 0; i < 8; ++i) { const float other = __shfl_xor(f0[i], 16), cs = rr[i], sn = rr[8 + i];
;             if (lg == 0) f0[i] = f0[i] * cs - other * sn; else if (lg == 1) f0[i] = f0[i] * cs + other * sn; }
; #pragma unroll
;         for (int i = 0; i < 8; ++i) { f0[i] *= 0.18033688011112042f; f1[i] *= 0.18033688011112042f; }
;         const bf16x8 qf0 = __builtin_bit_cast(bf16x8, pack8(f0)), qf1 = __builtin_bit_cast(bf16x8, pack8(f1));
.LBB0_319:
	v_lshlrev_b32_e32 v56, 16, v26
	v_and_b32_e32 v57, 0xffff0000, v26
	v_lshlrev_b32_e32 v34, 16, v30
	v_and_b32_e32 v35, 0xffff0000, v30
	v_lshlrev_b32_e32 v52, 16, v27
	v_and_b32_e32 v53, 0xffff0000, v27
	v_pk_mul_f32 v[26:27], v[56:57], v[56:57]
	v_lshlrev_b32_e32 v54, 16, v31
	v_and_b32_e32 v55, 0xffff0000, v31
	v_lshlrev_b32_e32 v48, 16, v28
	v_and_b32_e32 v49, 0xffff0000, v28
	v_lshlrev_b32_e32 v42, 16, v29
	v_and_b32_e32 v43, 0xffff0000, v29
	v_pk_fma_f32 v[26:27], v[34:35], v[34:35], v[26:27]
	v_pk_mul_f32 v[28:29], v[52:53], v[52:53]
	v_add_f32_e32 v26, v26, v27
	v_pk_fma_f32 v[28:29], v[54:55], v[54:55], v[28:29]
	v_lshlrev_b32_e32 v50, 16, v32
	v_and_b32_e32 v51, 0xffff0000, v32
	v_pk_mul_f32 v[30:31], v[48:49], v[48:49]
	v_add_f32_e32 v26, v28, v26
	v_pk_fma_f32 v[30:31], v[50:51], v[50:51], v[30:31]
	v_add_f32_e32 v26, v29, v26
	v_lshlrev_b32_e32 v44, 16, v33
	v_and_b32_e32 v45, 0xffff0000, v33
	v_pk_mul_f32 v[32:33], v[42:43], v[42:43]
	v_add_f32_e32 v26, v30, v26
	v_pk_fma_f32 v[32:33], v[44:45], v[44:45], v[32:33]
	v_add_f32_e32 v26, v31, v26
	v_add_f32_e32 v26, v32, v26
	v_add_f32_e32 v26, v33, v26
	v_mov_b32_e32 v27, v26
	v_readlane_b32 s20, v254, 25
	v_ashrrev_i32_e32 v103, 31, v102
	v_readlane_b32 s21, v254, 26
	s_mov_b64 s[38:39], -1
	v_permlane16_swap_b32_e32 v27, v26
	v_add_f32_e32 v26, v26, v27
	v_mov_b32_e32 v27, v26
	v_lshl_add_u64 v[242:243], v[102:103], 2, s[20:21]
	v_add_u32_e32 v103, 0, v108
	v_permlane32_swap_b32_e32 v27, v26
	v_add_f32_e32 v26, v26, v27
	v_fmamk_f32 v26, v26, 0x3c800000, v205
	v_cmp_gt_f32_e32 vcc, s79, v26
	v_mul_f32_e32 v27, 0x4b800000, v26
	s_nop 0
	v_cndmask_b32_e32 v26, v26, v27, vcc
	v_rsq_f32_e32 v26, v26
	s_nop 0
	v_mul_f32_e32 v27, 0x45800000, v26
	v_cndmask_b32_e32 v46, v26, v27, vcc
	v_pk_mul_f32 v[26:27], v[6:7], v[46:47] op_sel_hi:[1,0]
	s_andn2_b64 vcc, exec, s[36:37]
	v_pk_mul_f32 v[58:59], v[26:27], v[34:35]
	ds_bpermute_b32 v60, v104, v58
	ds_bpermute_b32 v61, v104, v59
	ds_read_b128 v[66:69], v103 offset:20800
	ds_read_b128 v[70:73], v103 offset:23104
	ds_read_b128 v[74:77], v103 offset:25408
	ds_read_b128 v[78:81], v103 offset:27712
	ds_read_b128 v[82:85], v103 offset:30016
	ds_read_b128 v[86:89], v103 offset:32320
	ds_read_b128 v[110:113], v103 offset:34624
	v_pk_mul_f32 v[226:227], v[226:227], v[58:59]
	s_waitcnt lgkmcnt(7)
	v_pk_fma_f32 v[62:63], v[234:235], v[60:61], v[226:227] neg_lo:[1,0,0] neg_hi:[1,0,0]
	v_pk_fma_f32 v[234:235], v[234:235], v[60:61], v[226:227]
	v_pk_mul_f32 v[38:39], v[14:15], v[46:47] op_sel_hi:[1,0]
	v_cndmask_b32_e64 v234, v58, v234, s[44:45]
	v_pk_mul_f32 v[38:39], v[38:39], v[56:57]
	v_pk_mul_f32 v[56:57], v[8:9], v[46:47] op_sel_hi:[1,0]
	v_cndmask_b32_e64 v235, v59, v235, s[44:45]
	v_pk_mul_f32 v[54:55], v[56:57], v[54:55]
	ds_bpermute_b32 v56, v104, v54
	ds_bpermute_b32 v57, v104, v55
	v_cndmask_b32_e64 v235, v235, v63, s[42:43]
	v_cndmask_b32_e64 v234, v234, v62, s[42:43]
	v_pk_mul_f32 v[234:235], v[234:235], s[78:79] op_sel_hi:[1,0]
	v_pk_mul_f32 v[38:39], v[38:39], s[78:79] op_sel_hi:[1,0]
	s_waitcnt lgkmcnt(0)
	v_pk_mul_f32 v[236:237], v[236:237], v[56:57]
	v_cvt_pk_bf16_f32 v94, v234, v235
	v_pk_fma_f32 v[56:57], v[228:229], v[54:55], v[236:237] neg_lo:[0,0,1] neg_hi:[0,0,1]
	v_pk_fma_f32 v[236:237], v[228:229], v[54:55], v[236:237]
	v_pk_mul_f32 v[40:41], v[16:17], v[46:47] op_sel_hi:[1,0]
	v_cndmask_b32_e64 v236, v54, v236, s[44:45]
	v_pk_mul_f32 v[40:41], v[40:41], v[52:53]
	v_pk_mul_f32 v[52:53], v[2:3], v[46:47] op_sel_hi:[1,0]
	v_cndmask_b32_e64 v237, v55, v237, s[44:45]
	v_pk_mul_f32 v[50:51], v[52:53], v[50:51]
	ds_bpermute_b32 v52, v104, v50
	ds_bpermute_b32 v53, v104, v51
	v_cndmask_b32_e64 v237, v237, v57, s[42:43]
	v_cndmask_b32_e64 v236, v236, v56, s[42:43]
	v_pk_mul_f32 v[236:237], v[236:237], s[78:79] op_sel_hi:[1,0]
	v_pk_mul_f32 v[40:41], v[40:41], s[78:79] op_sel_hi:[1,0]
	s_waitcnt lgkmcnt(0)
	v_pk_mul_f32 v[238:239], v[238:239], v[52:53]
	v_cvt_pk_bf16_f32 v95, v236, v237
	v_pk_fma_f32 v[52:53], v[50:51], v[230:231], v[238:239] neg_lo:[0,0,1] neg_hi:[0,0,1]
	v_pk_fma_f32 v[238:239], v[50:51], v[230:231], v[238:239]
	v_pk_mul_f32 v[30:31], v[10:11], v[46:47] op_sel_hi:[1,0]
	v_cndmask_b32_e64 v238, v50, v238, s[44:45]
	v_pk_mul_f32 v[30:31], v[30:31], v[48:49]
	v_pk_mul_f32 v[48:49], v[4:5], v[46:47] op_sel_hi:[1,0]
	v_cndmask_b32_e64 v239, v51, v239, s[44:45]
	v_pk_mul_f32 v[44:45], v[48:49], v[44:45]
	ds_bpermute_b32 v48, v104, v44
	ds_bpermute_b32 v49, v104, v45
	v_cndmask_b32_e64 v239, v239, v53, s[42:43]
	v_cndmask_b32_e64 v238, v238, v52, s[42:43]
	v_pk_mul_f32 v[238:239], v[238:239], s[78:79] op_sel_hi:[1,0]
	v_pk_mul_f32 v[30:31], v[30:31], s[78:79] op_sel_hi:[1,0]
	s_waitcnt lgkmcnt(0)
	v_pk_mul_f32 v[240:241], v[240:241], v[48:49]
	v_cvt_pk_bf16_f32 v96, v238, v239
	v_pk_fma_f32 v[48:49], v[44:45], v[232:233], v[240:241] neg_lo:[0,0,1] neg_hi:[0,0,1]
	v_pk_fma_f32 v[240:241], v[44:45], v[232:233], v[240:241]
	v_pk_mul_f32 v[32:33], v[12:13], v[46:47] op_sel_hi:[1,0]
	v_cndmask_b32_e64 v240, v44, v240, s[44:45]
	v_cndmask_b32_e64 v241, v45, v241, s[44:45]
	v_cndmask_b32_e64 v241, v241, v49, s[42:43]
	v_cndmask_b32_e64 v240, v240, v48, s[42:43]
	v_pk_mul_f32 v[240:241], v[240:241], s[78:79] op_sel_hi:[1,0]
	v_pk_mul_f32 v[32:33], v[32:33], v[42:43]
	v_cvt_pk_bf16_f32 v97, v240, v241
	s_cmp_eq_u32 s40, 48
	s_cbranch_scc1 .Lrope_pf_skip
	global_load_dwordx4 v[238:241], v[242:243], off offset:1072
	global_load_dwordx4 v[234:237], v[242:243], off offset:1056
	global_load_dwordx4 v[230:233], v[242:243], off offset:1040
	global_load_dwordx4 v[226:229], v[242:243], off offset:1024
